# incremental unit scheduling (pn+=4 carry pm+=8) replaces per-unit 64-bit/rcp StaticOrder::next in P1,P3-P6 when grid==256
# baseline (speedup 1.0000x reference)
;     __host__ __device__ bool next(int i, Unit& u) const {
;         const long L = (long)i * G + c; if (L >= nwg) return false;
;         int wgid = (int)L; { const int q = nwg / NXCD, r = nwg % NXCD, xcd = wgid % NXCD, off = wgid / NXCD; wgid = (xcd < r ? xcd * (q + 1) : r * (q + 1) + (xcd - r) * q) + off; }
;         const int nig = WGM * nN, gid = wgid / nig, fm = gid * WGM, gsz = (nM - fm) < WGM ? (nM - fm) : WGM;
;         u.pm = fm + ((wgid % nig) % gsz); u.pn = (wgid % nig) / gsz; return true;
;     }
; template <class Epi, class Sched, bool ALIGN_EPI = false, bool SP2 = false>
; __device__ __forceinline__ void gemm_phase(PG8_LAS unsigned char* lds, const Gemm g, const Sched& S, const Epi& E) {
;     ...
;         const bool has_next = S.next(ui + 1, nxt);
.LBB0_147:
	s_add_i32 s9, s9, 1
	s_cmpk_lg_i32 s33, 0x100
	s_cbranch_scc1 .Lp1_sched_gen
	s_cmp_lt_u32 s9, 17
	s_cselect_b64 s[4:5], -1, 0
	s_add_i32 s14, s70, 4
	s_mov_b32 s16, s22
	s_cmp_lt_u32 s14, 17
	s_cbranch_scc1 .LBB0_149
	s_sub_i32 s14, s14, 17
	s_add_i32 s16, s16, 8
	s_branch .LBB0_149
.Lp1_sched_gen:
	s_mul_i32 s4, s9, s8
	s_mul_hi_u32 s5, s9, s33
	s_add_i32 s5, s5, s4
	s_mul_i32 s4, s9, s33
	s_add_u32 s18, s4, s2
	s_addc_u32 s19, s5, s1
	v_cmp_gt_i64_e32 vcc, s[18:19], v[146:147]
	v_cmp_lt_i64_e64 s[4:5], s[18:19], v[144:145]
	s_cbranch_vccnz .LBB0_149
	s_ashr_i32 s14, s18, 31
	s_lshr_b32 s14, s14, 29
	s_add_i32 s14, s18, s14
	s_ashr_i32 s15, s14, 3
	s_and_b32 s14, s14, -8
	s_sub_i32 s14, s18, s14
	s_cmp_lt_i32 s14, 0
	s_cselect_b32 s16, s48, 0x220
	s_mul_i32 s14, s14, s16
	s_add_i32 s14, s14, s15
	s_mul_hi_i32 s15, s14, 0x78787879
	s_lshr_b32 s16, s15, 31
	s_ashr_i32 s15, s15, 6
	s_add_i32 s15, s15, s16
	s_lshl_b32 s16, s15, 3
	s_sub_i32 s17, 0x100, s16
	s_min_i32 s17, s17, 8
	s_abs_i32 s18, s17
	v_cvt_f32_u32_e32 v2, s18
	s_sub_i32 s20, 0, s18
	s_mulk_i32 s15, 0x88
	s_sub_i32 s15, s14, s15
	v_rcp_iflag_f32_e32 v2, v2
	s_abs_i32 s14, s15
	s_xor_b32 s19, s15, s17
	s_ashr_i32 s19, s19, 31
	v_mul_f32_e32 v2, 0x4f7ffffe, v2
	v_cvt_u32_f32_e32 v2, v2
	s_nop 0
	v_readfirstlane_b32 s21, v2
	s_mul_i32 s20, s20, s21
	s_mul_hi_u32 s20, s21, s20
	s_add_i32 s21, s21, s20
	s_mul_hi_u32 s20, s14, s21
	s_mul_i32 s21, s20, s18
	s_sub_i32 s14, s14, s21
	s_add_i32 s28, s20, 1
	s_sub_i32 s21, s14, s18
	s_cmp_ge_u32 s14, s18
	s_cselect_b32 s20, s28, s20
	s_cselect_b32 s14, s21, s14
	s_add_i32 s21, s20, 1
	s_cmp_ge_u32 s14, s18
	s_cselect_b32 s14, s21, s20
	s_xor_b32 s14, s14, s19
	s_sub_i32 s14, s14, s19
	s_mul_i32 s17, s14, s17
	s_sub_i32 s15, s15, s17
	s_add_i32 s16, s16, s15

;     __host__ __device__ bool next(int i, Unit& u) const {
;         const long L = (long)i * G + c; if (L >= nwg) return false;
;         int wgid = (int)L; { const int q = nwg / NXCD, r = nwg % NXCD, xcd = wgid % NXCD, off = wgid / NXCD; wgid = (xcd < r ? xcd * (q + 1) : r * (q + 1) + (xcd - r) * q) + off; }
;         const int nig = WGM * nN, gid = wgid / nig, fm = gid * WGM, gsz = (nM - fm) < WGM ? (nM - fm) : WGM;
;         u.pm = fm + ((wgid % nig) % gsz); u.pn = (wgid % nig) / gsz; return true;
;     }
; template <class Epi, class Sched, bool ALIGN_EPI = false, bool SP2 = false>
; __device__ __forceinline__ void gemm_phase(PG8_LAS unsigned char* lds, const Gemm g, const Sched& S, const Epi& E) {
;     ...
;         const bool has_next = S.next(ui + 1, nxt);
.LBB0_373:
	s_add_i32 s9, s9, 1
	s_cmpk_lg_i32 s33, 0x100
	s_cbranch_scc1 .Lp3_sched_gen
	s_cmp_lt_u32 s9, 4
	s_cselect_b64 s[4:5], -1, 0
	s_mov_b32 s18, s27
	s_add_i32 s20, s26, 8
	s_branch .LBB0_379
.Lp3_sched_gen:
	s_mul_i32 s0, s9, s8
	s_mul_hi_u32 s1, s9, s33
	s_add_i32 s1, s1, s0
	s_mul_i32 s0, s9, s33
	s_add_u32 s22, s0, s2
	s_addc_u32 s23, s1, s72
	v_cmp_gt_i64_e32 vcc, s[22:23], v[216:217]
	v_cmp_lt_i64_e64 s[4:5], s[22:23], v[214:215]
	s_cbranch_vccnz .LBB0_379
	s_ashr_i32 s0, s22, 31
	s_lshr_b32 s0, s0, 29
	s_add_i32 s0, s22, s0
	s_and_b32 s1, s0, -8
	s_sub_i32 s1, s22, s1
	s_cmp_gt_i32 s1, -1
	s_mov_b64 s[18:19], -1
	s_cbranch_scc0 .LBB0_376
	s_lshl_b32 s20, s1, 7
	s_mov_b64 s[18:19], 0

;     __host__ __device__ bool next(int i, Unit& u) const {
;         const long L = (long)i * G + c; if (L >= nwg) return false;
;         int wgid = (int)L; { const int q = nwg / NXCD, r = nwg % NXCD, xcd = wgid % NXCD, off = wgid / NXCD; wgid = (xcd < r ? xcd * (q + 1) : r * (q + 1) + (xcd - r) * q) + off; }
;         const int nig = WGM * nN, gid = wgid / nig, fm = gid * WGM, gsz = (nM - fm) < WGM ? (nM - fm) : WGM;
;         u.pm = fm + ((wgid % nig) % gsz); u.pn = (wgid % nig) / gsz; return true;
;     }
; template <class Epi, class Sched, bool ALIGN_EPI = false, bool SP2 = false>
; __device__ __forceinline__ void gemm_phase(PG8_LAS unsigned char* lds, const Gemm g, const Sched& S, const Epi& E) {
;     ...
;         const bool has_next = S.next(ui + 1, nxt);
.LBB0_470:
	s_add_i32 s11, s11, 1
	s_cmpk_lg_i32 s33, 0x100
	s_cbranch_scc1 .Lp4_sched_gen
	s_cmp_lt_u32 s11, 4
	s_cselect_b64 s[4:5], -1, 0
	s_mov_b32 s26, s48
	s_add_i32 s28, s46, 8
	s_branch .LBB0_476
.Lp4_sched_gen:
	s_mul_i32 s4, s11, s10
	s_mul_hi_u32 s5, s11, s33
	s_add_i32 s5, s5, s4
	s_mul_i32 s4, s11, s33
	s_add_u32 s42, s4, s2
	s_addc_u32 s43, s5, s75
	v_cmp_gt_i64_e32 vcc, s[42:43], v[194:195]
	v_cmp_lt_i64_e64 s[4:5], s[42:43], v[192:193]
	s_cbranch_vccnz .LBB0_476
	s_ashr_i32 s26, s42, 31
	s_lshr_b32 s26, s26, 29
	s_add_i32 s28, s42, s26
	s_and_b32 s26, s28, -8
	s_sub_i32 s29, s42, s26
	s_cmp_gt_i32 s29, -1
	s_mov_b64 s[26:27], -1
	s_cbranch_scc0 .LBB0_473
	s_lshl_b32 s42, s29, 7
	s_mov_b64 s[26:27], 0

;     __host__ __device__ bool next(int i, Unit& u) const {
;         const long L = (long)i * G + c; if (L >= nwg) return false;
;         int wgid = (int)L; { const int q = nwg / NXCD, r = nwg % NXCD, xcd = wgid % NXCD, off = wgid / NXCD; wgid = (xcd < r ? xcd * (q + 1) : r * (q + 1) + (xcd - r) * q) + off; }
;         const int nig = WGM * nN, gid = wgid / nig, fm = gid * WGM, gsz = (nM - fm) < WGM ? (nM - fm) : WGM;
;         u.pm = fm + ((wgid % nig) % gsz); u.pn = (wgid % nig) / gsz; return true;
;     }
; template <class Epi, class Sched, bool ALIGN_EPI = false, bool SP2 = false>
; __device__ __forceinline__ void gemm_phase(PG8_LAS unsigned char* lds, const Gemm g, const Sched& S, const Epi& E) {
;     ...
;         const bool has_next = S.next(ui + 1, nxt);
.LBB0_579:
	s_add_i32 s9, s9, 1
	s_cmpk_lg_i32 s33, 0x100
	s_cbranch_scc1 .Lp5_sched_gen
	s_cmp_lt_u32 s9, 16
	s_cselect_b64 s[4:5], -1, 0
	s_add_i32 s16, s25, 4
	s_mov_b32 s18, s24
	s_cmp_lt_u32 s16, 16
	s_cbranch_scc1 .LBB0_585
	s_sub_i32 s16, s16, 16
	s_add_i32 s18, s18, 8
	s_branch .LBB0_585
.Lp5_sched_gen:
	s_mul_i32 s4, s9, s51
	s_mul_hi_u32 s5, s9, s33
	s_add_i32 s5, s5, s4
	s_mul_i32 s4, s9, s33
	s_add_u32 s20, s4, s2
	s_addc_u32 s21, s5, s0
	v_cmp_gt_i64_e32 vcc, s[20:21], v[148:149]
	v_cmp_lt_i64_e64 s[4:5], s[20:21], v[146:147]
	s_cbranch_vccnz .LBB0_585
	s_ashr_i32 s16, s20, 31
	s_lshr_b32 s16, s16, 29
	s_add_i32 s18, s20, s16
	s_and_b32 s16, s18, -8
	s_sub_i32 s19, s20, s16
	s_cmp_gt_i32 s19, -1
	s_mov_b64 s[16:17], -1
	s_cbranch_scc0 .LBB0_582
	s_lshl_b32 s20, s19, 9
	s_mov_b64 s[16:17], 0

;     __host__ __device__ bool next(int i, Unit& u) const {
;         const long L = (long)i * G + c; if (L >= nwg) return false;
;         int wgid = (int)L; { const int q = nwg / NXCD, r = nwg % NXCD, xcd = wgid % NXCD, off = wgid / NXCD; wgid = (xcd < r ? xcd * (q + 1) : r * (q + 1) + (xcd - r) * q) + off; }
;         const int nig = WGM * nN, gid = wgid / nig, fm = gid * WGM, gsz = (nM - fm) < WGM ? (nM - fm) : WGM;
;         u.pm = fm + ((wgid % nig) % gsz); u.pn = (wgid % nig) / gsz; return true;
;     }
; template <class Epi, class Sched, bool ALIGN_EPI = false, bool SP2 = false>
; __device__ __forceinline__ void gemm_phase(PG8_LAS unsigned char* lds, const Gemm g, const Sched& S, const Epi& E) {
;     ...
;         const bool has_next = S.next(ui + 1, nxt);
.LBB0_675:
	s_add_i32 s15, s15, 1
	s_cmpk_lg_i32 s33, 0x100
	s_cbranch_scc1 .Lp6_sched_gen
	s_cmp_lt_u32 s15, 4
	s_cselect_b64 s[4:5], -1, 0
	s_mov_b32 s20, s8
	s_add_i32 s22, s28, 8
	s_branch .LBB0_681
.Lp6_sched_gen:
	s_mul_i32 s4, s15, s14
	s_mul_hi_u32 s5, s15, s33
	s_add_i32 s5, s5, s4
	s_mul_i32 s4, s15, s33
	s_add_u32 s24, s4, s2
	s_addc_u32 s25, s5, s58
	v_cmp_gt_i64_e32 vcc, s[24:25], v[204:205]
	v_cmp_lt_i64_e64 s[4:5], s[24:25], v[202:203]
	s_cbranch_vccnz .LBB0_681
	s_ashr_i32 s9, s24, 31
	s_lshr_b32 s9, s9, 29
	s_add_i32 s9, s24, s9
	s_and_b32 s20, s9, -8
	s_sub_i32 s22, s24, s20
	s_cmp_gt_i32 s22, -1
	s_mov_b64 s[20:21], -1
	s_cbranch_scc0 .LBB0_678
	s_lshl_b32 s23, s22, 7
	s_mov_b64 s[20:21], 0
